# diff-attention tile loops: DMA address increments, first two probability packs and zero-register restore moved into the shadows of the last P.V MFMAs; rescale block uses other temporaries
# baseline (speedup 1.0000x reference)
.Lmy_a_nov2:
	s_waitcnt lgkmcnt(4)
	v_mfma_f32_32x32x16_bf16 v[82:97], v[178:181], v[182:185], v[82:97]
	ds_read_b64_tr_b16 v[182:183], v253 offset:57600
	ds_read_b64_tr_b16 v[184:185], v253 offset:61696
	v_sub_f32_e32 v140, v140, v0
	v_exp_f32_e32 v140, v140
	v_add_f32_e32 v130, v139, v130
	s_waitcnt lgkmcnt(4)
	v_mfma_f32_32x32x16_bf16 v[66:81], v[178:181], v[248:251], v[66:81]
	ds_read_b64_tr_b16 v[248:249], v254 offset:57600
	ds_read_b64_tr_b16 v[250:251], v254 offset:61696
	v_sub_f32_e32 v141, v141, v0
	v_exp_f32_e32 v141, v141
	v_add_f32_e32 v130, v140, v130
	v_lshl_add_u64 v[204:205], v[204:205], 0, s[12:13]
	v_lshl_add_u64 v[206:207], v[206:207], 0, s[12:13]
	s_waitcnt lgkmcnt(4)
	v_mfma_f32_32x32x16_bf16 v[50:65], v[178:181], v[190:193], v[50:65]
	ds_read_b64_tr_b16 v[190:191], v195 offset:57600
	ds_read_b64_tr_b16 v[192:193], v195 offset:61696
	v_sub_f32_e32 v142, v142, v0
	v_exp_f32_e32 v142, v142
	v_add_f32_e32 v130, v141, v130
	v_lshl_add_u64 v[208:209], v[208:209], 0, s[8:9]
	v_lshl_add_u64 v[210:211], v[210:211], 0, s[8:9]
	s_waitcnt lgkmcnt(4)
	v_mfma_f32_32x32x16_bf16 v[34:49], v[178:181], v[182:185], v[34:49]
	v_sub_f32_e32 v143, v143, v0
	v_exp_f32_e32 v143, v143
	v_add_f32_e32 v130, v142, v130
	s_waitcnt lgkmcnt(2)
	v_mfma_f32_32x32x16_bf16 v[18:33], v[178:181], v[248:251], v[18:33]
	v_sub_f32_e32 v144, v144, v0
	v_exp_f32_e32 v144, v144
	v_add_f32_e32 v130, v143, v130
	v_cvt_pk_bf16_f32 v182, v1, v131
	v_mov_b32_e32 v1, 0
	v_cvt_pk_bf16_f32 v183, v132, v133
	s_waitcnt lgkmcnt(0)
	v_mfma_f32_32x32x16_bf16 v[2:17], v[178:181], v[190:193], v[2:17]
	v_sub_f32_e32 v145, v145, v0
	v_exp_f32_e32 v145, v145
	v_add_f32_e32 v130, v144, v130
	s_cbranch_vccz .LBB0_295
	ds_write_b32 v226, v247
	ds_read_b128 v[190:193], v227 offset:96
	ds_read_b128 v[186:189], v227 offset:64
	ds_read_b128 v[248:251], v227 offset:32
	ds_read_b128 v[214:217], v227
	s_waitcnt lgkmcnt(3)
	v_pk_mul_f32 v[128:129], v[128:129], v[192:193]
	s_waitcnt lgkmcnt(2)
	v_pk_mul_f32 v[124:125], v[124:125], v[188:189]
	s_waitcnt lgkmcnt(1)
	v_pk_mul_f32 v[120:121], v[120:121], v[250:251]
	s_waitcnt lgkmcnt(0)
	v_pk_mul_f32 v[116:117], v[116:117], v[216:217]
	v_pk_mul_f32 v[126:127], v[126:127], v[190:191]
	v_pk_mul_f32 v[122:123], v[122:123], v[186:187]
	v_pk_mul_f32 v[118:119], v[118:119], v[248:249]
	v_pk_mul_f32 v[114:115], v[114:115], v[214:215]
	v_pk_mul_f32 v[112:113], v[112:113], v[192:193]
	v_pk_mul_f32 v[108:109], v[108:109], v[188:189]
	v_pk_mul_f32 v[104:105], v[104:105], v[250:251]
	v_pk_mul_f32 v[100:101], v[100:101], v[216:217]
	v_pk_mul_f32 v[110:111], v[110:111], v[190:191]
	v_pk_mul_f32 v[106:107], v[106:107], v[186:187]
	v_pk_mul_f32 v[102:103], v[102:103], v[248:249]
	v_pk_mul_f32 v[98:99], v[98:99], v[214:215]
	v_pk_mul_f32 v[96:97], v[96:97], v[192:193]
	v_pk_mul_f32 v[92:93], v[92:93], v[188:189]
	v_pk_mul_f32 v[88:89], v[88:89], v[250:251]
	v_pk_mul_f32 v[84:85], v[84:85], v[216:217]
	v_pk_mul_f32 v[94:95], v[94:95], v[190:191]
	v_pk_mul_f32 v[90:91], v[90:91], v[186:187]
	v_pk_mul_f32 v[86:87], v[86:87], v[248:249]
	v_pk_mul_f32 v[82:83], v[82:83], v[214:215]
	v_pk_mul_f32 v[80:81], v[80:81], v[192:193]
	v_pk_mul_f32 v[76:77], v[76:77], v[188:189]
	v_pk_mul_f32 v[72:73], v[72:73], v[250:251]
	v_pk_mul_f32 v[68:69], v[68:69], v[216:217]
	v_pk_mul_f32 v[78:79], v[78:79], v[190:191]
	v_pk_mul_f32 v[74:75], v[74:75], v[186:187]
	v_pk_mul_f32 v[70:71], v[70:71], v[248:249]
	v_pk_mul_f32 v[66:67], v[66:67], v[214:215]
	v_pk_mul_f32 v[64:65], v[64:65], v[192:193]
	v_pk_mul_f32 v[60:61], v[60:61], v[188:189]
	v_pk_mul_f32 v[56:57], v[56:57], v[250:251]
	v_pk_mul_f32 v[52:53], v[52:53], v[216:217]
	v_pk_mul_f32 v[62:63], v[62:63], v[190:191]
	v_pk_mul_f32 v[58:59], v[58:59], v[186:187]
	v_pk_mul_f32 v[54:55], v[54:55], v[248:249]
	v_pk_mul_f32 v[50:51], v[50:51], v[214:215]
	v_pk_mul_f32 v[48:49], v[48:49], v[192:193]
	v_pk_mul_f32 v[44:45], v[44:45], v[188:189]
	v_pk_mul_f32 v[40:41], v[40:41], v[250:251]
	v_pk_mul_f32 v[36:37], v[36:37], v[216:217]
	v_pk_mul_f32 v[46:47], v[46:47], v[190:191]
	v_pk_mul_f32 v[42:43], v[42:43], v[186:187]
	v_pk_mul_f32 v[38:39], v[38:39], v[248:249]
	v_pk_mul_f32 v[34:35], v[34:35], v[214:215]
	v_pk_mul_f32 v[32:33], v[32:33], v[192:193]
	v_pk_mul_f32 v[28:29], v[28:29], v[188:189]
	v_pk_mul_f32 v[24:25], v[24:25], v[250:251]
	v_pk_mul_f32 v[20:21], v[20:21], v[216:217]
	v_pk_mul_f32 v[30:31], v[30:31], v[190:191]
	v_pk_mul_f32 v[26:27], v[26:27], v[186:187]
	v_pk_mul_f32 v[22:23], v[22:23], v[248:249]
	v_pk_mul_f32 v[18:19], v[18:19], v[214:215]
	v_pk_mul_f32 v[16:17], v[16:17], v[192:193]
	v_pk_mul_f32 v[12:13], v[12:13], v[188:189]
	v_pk_mul_f32 v[8:9], v[8:9], v[250:251]
	v_pk_mul_f32 v[4:5], v[4:5], v[216:217]
	v_pk_mul_f32 v[14:15], v[14:15], v[190:191]
	v_pk_mul_f32 v[10:11], v[10:11], v[186:187]
	v_pk_mul_f32 v[6:7], v[6:7], v[248:249]
	v_pk_mul_f32 v[2:3], v[2:3], v[214:215]
.LBB0_295:
	v_add_f32_e32 v130, v145, v130
	s_add_i32 s0, s48, 1
	s_cmp_lg_u32 s48, 2
	s_cselect_b32 s0, s0, 0
	s_add_i32 s46, s46, 32
	s_add_i32 s47, s47, 1
	v_fmac_f32_e32 v130, v203, v247
	v_cvt_pk_bf16_f32 v184, v134, v135
	v_cvt_pk_bf16_f32 v185, v136, v137
	v_cvt_pk_bf16_f32 v178, v138, v139
	v_cvt_pk_bf16_f32 v179, v140, v141
	v_cvt_pk_bf16_f32 v180, v142, v143
	v_cvt_pk_bf16_f32 v181, v144, v145
	s_cmp_eq_u32 s45, s46
	s_cbranch_scc1 .LBB0_297
	v_mov_b32_e32 v203, v130
	v_mov_b32_e32 v186, v0
	s_mov_b32 s49, s48
	s_branch .LBB0_281

.LBB0_1619:
	v_add_f32_e32 v130, v145, v130
	s_add_i32 s0, s46, 1
	s_cmp_lg_u32 s46, 2
	s_cselect_b32 s0, s0, 0
	s_add_i32 s44, s44, 32
	s_add_i32 s45, s45, 1
	v_fmac_f32_e32 v130, v203, v247
	v_cvt_pk_bf16_f32 v184, v134, v135
	v_cvt_pk_bf16_f32 v185, v136, v137
	v_cvt_pk_bf16_f32 v178, v138, v139
	v_cvt_pk_bf16_f32 v179, v140, v141
	v_cvt_pk_bf16_f32 v180, v142, v143
	v_cvt_pk_bf16_f32 v181, v144, v145
	s_cmp_eq_u32 s43, s44
	s_cbranch_scc1 .LBB0_1621
	v_mov_b32_e32 v203, v130
	v_mov_b32_e32 v186, v0
	s_mov_b32 s47, s46
	s_branch .LBB0_1605
